# nt hint on the once-read f32 weight loads of the next-layer weight conversion items (P9 tail), on top of nt output stores for P2 and P8
# speedup vs baseline: 1.0033x; 1.0033x over previous
.LBB0_54:
	s_sub_i32 s3, s6, s10
	s_cmpk_gt_i32 s3, 0x5ff
	s_cbranch_scc0 .LBB0_64
	s_cmpk_gt_u32 s3, 0x77f
	s_cbranch_scc0 .LBB0_61
	s_lshl_b32 s2, s3, 6
	s_cmpk_gt_u32 s3, 0x87f
	s_cbranch_scc0 .LBB0_58
	s_lshl_b32 s0, s3, 1
	s_add_i32 s0, s0, 0x1ef00
	v_mov_b32_e32 v7, v211
	s_and_b32 s1, s0, 0x1ffc0
	s_and_b32 s0, s2, 0x7c0
	s_lshl_b32 s4, s0, 2
	v_readlane_b32 s5, v254, 26
	v_ashrrev_i32_e32 v15, 6, v7
	v_and_b32_e32 v14, 63, v7
	s_add_u32 s4, s5, s4
	v_readlane_b32 s5, v254, 27
	v_add_u32_e32 v2, s1, v15
	s_addc_u32 s5, s5, 0
	v_lshlrev_b32_e32 v208, 2, v14
	v_ashrrev_i32_e32 v3, 31, v2
	v_lshl_add_u64 v[0:1], s[4:5], 0, v[208:209]
	v_lshlrev_b64 v[2:3], 13, v[2:3]
	v_lshl_add_u64 v[2:3], v[0:1], 0, v[2:3]
	global_load_dword v16, v[2:3], off nt
	v_add_u32_e32 v2, 0x100, v7
	v_ashrrev_i32_e32 v17, 6, v2
	v_add_u32_e32 v2, s1, v17
	v_ashrrev_i32_e32 v3, 31, v2
	v_lshlrev_b64 v[2:3], 13, v[2:3]
	v_lshl_add_u64 v[2:3], v[0:1], 0, v[2:3]
	global_load_dword v18, v[2:3], off nt
	v_add_u32_e32 v2, 0x200, v7
	v_ashrrev_i32_e32 v19, 6, v2
	v_add_u32_e32 v2, s1, v19
	v_ashrrev_i32_e32 v3, 31, v2
	v_lshlrev_b64 v[2:3], 13, v[2:3]
	v_lshl_add_u64 v[2:3], v[0:1], 0, v[2:3]
	global_load_dword v20, v[2:3], off nt
	v_add_u32_e32 v2, 0x300, v7
	v_ashrrev_i32_e32 v21, 6, v2
	v_add_u32_e32 v2, s1, v21
	v_ashrrev_i32_e32 v3, 31, v2
	v_lshlrev_b64 v[2:3], 13, v[2:3]
	v_lshl_add_u64 v[2:3], v[0:1], 0, v[2:3]
	global_load_dword v22, v[2:3], off nt
	v_add_u32_e32 v2, 0x400, v7
	v_ashrrev_i32_e32 v23, 6, v2
	v_add_u32_e32 v2, s1, v23
	v_ashrrev_i32_e32 v3, 31, v2
	v_lshlrev_b64 v[2:3], 13, v[2:3]
	v_lshl_add_u64 v[2:3], v[0:1], 0, v[2:3]
	global_load_dword v24, v[2:3], off nt
	v_add_u32_e32 v2, 0x500, v7
	v_ashrrev_i32_e32 v25, 6, v2
	v_add_u32_e32 v2, s1, v25
	v_ashrrev_i32_e32 v3, 31, v2
	v_lshlrev_b64 v[2:3], 13, v[2:3]
	v_lshl_add_u64 v[2:3], v[0:1], 0, v[2:3]
	global_load_dword v26, v[2:3], off nt
	v_add_u32_e32 v2, 0x600, v7
	v_ashrrev_i32_e32 v27, 6, v2
	v_add_u32_e32 v2, s1, v27
	v_ashrrev_i32_e32 v3, 31, v2
	v_lshlrev_b64 v[2:3], 13, v[2:3]
	v_lshl_add_u64 v[2:3], v[0:1], 0, v[2:3]
	global_load_dword v28, v[2:3], off nt
	v_add_u32_e32 v2, 0x700, v7
	v_ashrrev_i32_e32 v9, 6, v2
	v_add_u32_e32 v2, s1, v9
	v_ashrrev_i32_e32 v3, 31, v2
	v_lshlrev_b64 v[2:3], 13, v[2:3]
	v_lshl_add_u64 v[2:3], v[0:1], 0, v[2:3]
	global_load_dword v29, v[2:3], off nt
	v_add_u32_e32 v2, 0x800, v7
	v_ashrrev_i32_e32 v11, 6, v2
	v_add_u32_e32 v2, s1, v11
	v_ashrrev_i32_e32 v3, 31, v2
	v_lshlrev_b64 v[2:3], 13, v[2:3]
	v_lshl_add_u64 v[2:3], v[0:1], 0, v[2:3]
	global_load_dword v30, v[2:3], off nt
	v_add_u32_e32 v2, 0x900, v7
	v_ashrrev_i32_e32 v10, 6, v2
	v_add_u32_e32 v2, s1, v10
	v_ashrrev_i32_e32 v3, 31, v2
	v_lshlrev_b64 v[2:3], 13, v[2:3]
	v_lshl_add_u64 v[2:3], v[0:1], 0, v[2:3]
	global_load_dword v31, v[2:3], off nt
	v_add_u32_e32 v2, 0xa00, v7
	v_ashrrev_i32_e32 v8, 6, v2
	v_add_u32_e32 v2, s1, v8
	v_ashrrev_i32_e32 v3, 31, v2
	v_lshlrev_b64 v[2:3], 13, v[2:3]
	v_lshl_add_u64 v[2:3], v[0:1], 0, v[2:3]
	global_load_dword v32, v[2:3], off nt
	v_add_u32_e32 v2, 0xb00, v7
	v_ashrrev_i32_e32 v6, 6, v2
	v_add_u32_e32 v2, s1, v6
	v_ashrrev_i32_e32 v3, 31, v2
	v_lshlrev_b64 v[2:3], 13, v[2:3]
	v_lshl_add_u64 v[2:3], v[0:1], 0, v[2:3]
	global_load_dword v33, v[2:3], off nt
	v_add_u32_e32 v2, 0xc00, v7
	v_ashrrev_i32_e32 v5, 6, v2
	v_add_u32_e32 v2, s1, v5
	v_ashrrev_i32_e32 v3, 31, v2
	v_lshlrev_b64 v[2:3], 13, v[2:3]
	v_lshl_add_u64 v[2:3], v[0:1], 0, v[2:3]
	global_load_dword v34, v[2:3], off nt
	v_add_u32_e32 v2, 0xd00, v7
	v_ashrrev_i32_e32 v4, 6, v2
	v_add_u32_e32 v2, s1, v4
	v_ashrrev_i32_e32 v3, 31, v2
	v_lshlrev_b64 v[2:3], 13, v[2:3]
	v_lshl_add_u64 v[2:3], v[0:1], 0, v[2:3]
	global_load_dword v35, v[2:3], off nt
	v_add_u32_e32 v2, 0xe00, v7
	v_ashrrev_i32_e32 v3, 6, v2
	v_add_u32_e32 v12, s1, v3
	v_ashrrev_i32_e32 v13, 31, v12
	v_lshlrev_b64 v[12:13], 13, v[12:13]
	v_add_u32_e32 v2, 0xf00, v7
	v_lshl_add_u64 v[12:13], v[0:1], 0, v[12:13]
	v_ashrrev_i32_e32 v2, 6, v2
	global_load_dword v36, v[12:13], off nt
	v_add_u32_e32 v12, s1, v2
	v_ashrrev_i32_e32 v13, 31, v12
	v_lshlrev_b64 v[12:13], 13, v[12:13]
	v_lshl_add_u64 v[0:1], v[0:1], 0, v[12:13]
	global_load_dword v7, v[0:1], off nt
	v_add_u32_e32 v0, 0, v208
	v_mad_u64_u32 v[12:13], s[4:5], v15, s24, v[0:1]
	s_waitcnt vmcnt(15)
	ds_write_b32 v12, v16
	v_mad_u64_u32 v[12:13], s[4:5], v17, s24, v[0:1]
	s_waitcnt vmcnt(14)
	ds_write_b32 v12, v18
	v_mad_u64_u32 v[12:13], s[4:5], v19, s24, v[0:1]
	s_waitcnt vmcnt(13)
	ds_write_b32 v12, v20
	v_mad_u64_u32 v[12:13], s[4:5], v21, s24, v[0:1]
	s_waitcnt vmcnt(12)
	ds_write_b32 v12, v22
	v_mad_u64_u32 v[12:13], s[4:5], v23, s24, v[0:1]
	s_waitcnt vmcnt(11)
	ds_write_b32 v12, v24
	v_mad_u64_u32 v[12:13], s[4:5], v25, s24, v[0:1]
	s_waitcnt vmcnt(10)
	ds_write_b32 v12, v26
	v_mad_u64_u32 v[12:13], s[4:5], v27, s24, v[0:1]
	s_waitcnt vmcnt(9)
	ds_write_b32 v12, v28
	v_mad_u64_u32 v[12:13], s[4:5], v9, s24, v[0:1]
	s_waitcnt vmcnt(8)
	ds_write_b32 v12, v29
	v_mad_u64_u32 v[12:13], s[4:5], v11, s24, v[0:1]
	s_lshl_b32 s1, s1, 1
	v_lshlrev_b32_e32 v208, 1, v14
	s_waitcnt vmcnt(7)
	ds_write_b32 v12, v30
	v_mad_u64_u32 v[12:13], s[4:5], v10, s24, v[0:1]
	s_waitcnt vmcnt(6)
	ds_write_b32 v12, v31
	v_mad_u64_u32 v[12:13], s[4:5], v8, s24, v[0:1]
	s_waitcnt vmcnt(5)
	ds_write_b32 v12, v32
	v_mad_u64_u32 v[12:13], s[4:5], v6, s24, v[0:1]
	s_waitcnt vmcnt(4)
	ds_write_b32 v12, v33
	v_mad_u64_u32 v[12:13], s[4:5], v5, s24, v[0:1]
	s_waitcnt vmcnt(3)
	ds_write_b32 v12, v34
	v_mad_u64_u32 v[12:13], s[4:5], v4, s24, v[0:1]
	s_waitcnt vmcnt(2)
	ds_write_b32 v12, v35
	v_mad_u64_u32 v[12:13], s[4:5], v3, s24, v[0:1]
	v_mad_u64_u32 v[0:1], s[4:5], v2, s24, v[0:1]
	v_readlane_b32 s4, v252, 9
	s_add_u32 s4, s4, s1
	v_readlane_b32 s1, v252, 10
	s_addc_u32 s5, s1, 0
	s_waitcnt vmcnt(1)
	ds_write_b32 v12, v36
	s_waitcnt vmcnt(0)
	ds_write_b32 v0, v7
	v_mad_u32_u24 v7, v14, s24, 0
	v_lshl_add_u32 v0, v15, 2, v7
	s_waitcnt lgkmcnt(0)
	s_barrier
	ds_read_b32 v12, v0
	v_lshl_add_u32 v13, v17, 2, v7
	v_lshl_add_u64 v[0:1], s[4:5], 0, v[208:209]
	s_waitcnt lgkmcnt(0)
	v_cvt_pk_bf16_f32 v14, v12, s0
	v_add_u32_e32 v12, s0, v15
	ds_read_b32 v15, v13
	v_ashrrev_i32_e32 v13, 31, v12
	v_lshlrev_b64 v[12:13], 11, v[12:13]
	v_lshl_add_u64 v[12:13], v[0:1], 0, v[12:13]
	global_store_short v[12:13], v14, off
	v_lshl_add_u32 v13, v19, 2, v7
	s_waitcnt lgkmcnt(0)
	v_cvt_pk_bf16_f32 v14, v15, s0
	v_add_u32_e32 v12, s0, v17
	ds_read_b32 v15, v13
	v_ashrrev_i32_e32 v13, 31, v12
	v_lshlrev_b64 v[12:13], 11, v[12:13]
	v_lshl_add_u64 v[12:13], v[0:1], 0, v[12:13]
	global_store_short v[12:13], v14, off
	v_lshl_add_u32 v13, v21, 2, v7
	s_waitcnt lgkmcnt(0)
	v_cvt_pk_bf16_f32 v14, v15, s0
	v_add_u32_e32 v12, s0, v19
	ds_read_b32 v15, v13
	v_ashrrev_i32_e32 v13, 31, v12
	v_lshlrev_b64 v[12:13], 11, v[12:13]
	v_lshl_add_u64 v[12:13], v[0:1], 0, v[12:13]
	global_store_short v[12:13], v14, off
	v_lshl_add_u32 v13, v23, 2, v7
	s_waitcnt lgkmcnt(0)
	v_cvt_pk_bf16_f32 v14, v15, s0
	v_add_u32_e32 v12, s0, v21
	ds_read_b32 v15, v13
	v_ashrrev_i32_e32 v13, 31, v12
	v_lshlrev_b64 v[12:13], 11, v[12:13]
	v_lshl_add_u64 v[12:13], v[0:1], 0, v[12:13]
	global_store_short v[12:13], v14, off
	v_lshl_add_u32 v13, v25, 2, v7
	s_waitcnt lgkmcnt(0)
	v_cvt_pk_bf16_f32 v14, v15, s0
	v_add_u32_e32 v12, s0, v23
	ds_read_b32 v15, v13
	v_ashrrev_i32_e32 v13, 31, v12
	v_lshlrev_b64 v[12:13], 11, v[12:13]
	v_lshl_add_u64 v[12:13], v[0:1], 0, v[12:13]
	global_store_short v[12:13], v14, off
	v_lshl_add_u32 v13, v27, 2, v7
	s_waitcnt lgkmcnt(0)
	v_cvt_pk_bf16_f32 v14, v15, s0
	v_add_u32_e32 v12, s0, v25
	ds_read_b32 v15, v13
	v_ashrrev_i32_e32 v13, 31, v12
	v_lshlrev_b64 v[12:13], 11, v[12:13]
	v_lshl_add_u64 v[12:13], v[0:1], 0, v[12:13]
	global_store_short v[12:13], v14, off
	v_add_u32_e32 v12, s0, v27
	v_lshl_add_u32 v13, v9, 2, v7
	s_waitcnt lgkmcnt(0)
	v_cvt_pk_bf16_f32 v14, v15, s0
	ds_read_b32 v15, v13
	v_ashrrev_i32_e32 v13, 31, v12
	v_lshlrev_b64 v[12:13], 11, v[12:13]
	v_lshl_add_u64 v[12:13], v[0:1], 0, v[12:13]
	global_store_short v[12:13], v14, off
	v_add_u32_e32 v12, s0, v9
	v_ashrrev_i32_e32 v13, 31, v12
	v_lshlrev_b64 v[12:13], 11, v[12:13]
	s_waitcnt lgkmcnt(0)
	v_cvt_pk_bf16_f32 v14, v15, s0
	v_lshl_add_u32 v9, v11, 2, v7
	v_lshl_add_u64 v[12:13], v[0:1], 0, v[12:13]
	ds_read_b32 v9, v9
	global_store_short v[12:13], v14, off
	v_add_u32_e32 v12, s0, v11
	v_lshl_add_u32 v11, v10, 2, v7
	ds_read_b32 v11, v11
	v_ashrrev_i32_e32 v13, 31, v12
	v_lshlrev_b64 v[12:13], 11, v[12:13]
	s_waitcnt lgkmcnt(1)
	v_cvt_pk_bf16_f32 v9, v9, s0
	v_lshl_add_u64 v[12:13], v[0:1], 0, v[12:13]
	global_store_short v[12:13], v9, off
	s_waitcnt lgkmcnt(0)
	v_cvt_pk_bf16_f32 v9, v11, s0
	v_add_u32_e32 v10, s0, v10
	v_lshl_add_u32 v11, v8, 2, v7
	ds_read_b32 v12, v11
	v_ashrrev_i32_e32 v11, 31, v10
	v_lshlrev_b64 v[10:11], 11, v[10:11]
	v_lshl_add_u64 v[10:11], v[0:1], 0, v[10:11]
	global_store_short v[10:11], v9, off
	v_add_u32_e32 v8, s0, v8
	v_lshl_add_u32 v9, v6, 2, v7
	ds_read_b32 v11, v9
	v_ashrrev_i32_e32 v9, 31, v8
	v_lshlrev_b64 v[8:9], 11, v[8:9]
	s_waitcnt lgkmcnt(1)
	v_cvt_pk_bf16_f32 v10, v12, s0
	v_lshl_add_u64 v[8:9], v[0:1], 0, v[8:9]
	global_store_short v[8:9], v10, off
	v_add_u32_e32 v8, s0, v6
	v_ashrrev_i32_e32 v9, 31, v8
	v_lshlrev_b64 v[8:9], 11, v[8:9]
	s_waitcnt lgkmcnt(0)
	v_cvt_pk_bf16_f32 v10, v11, s0
	v_lshl_add_u32 v6, v5, 2, v7
	v_lshl_add_u64 v[8:9], v[0:1], 0, v[8:9]
	ds_read_b32 v6, v6
	global_store_short v[8:9], v10, off
	v_add_u32_e32 v8, s0, v5
	v_lshl_add_u32 v5, v4, 2, v7
	ds_read_b32 v5, v5
	v_ashrrev_i32_e32 v9, 31, v8
	v_lshlrev_b64 v[8:9], 11, v[8:9]
	s_waitcnt lgkmcnt(1)
	v_cvt_pk_bf16_f32 v6, v6, s0
	v_lshl_add_u64 v[8:9], v[0:1], 0, v[8:9]
	global_store_short v[8:9], v6, off
	s_waitcnt lgkmcnt(0)
	v_cvt_pk_bf16_f32 v6, v5, s0
	v_add_u32_e32 v4, s0, v4
	v_lshl_add_u32 v5, v3, 2, v7
	ds_read_b32 v8, v5
	v_ashrrev_i32_e32 v5, 31, v4
	v_lshlrev_b64 v[4:5], 11, v[4:5]
	v_lshl_add_u64 v[4:5], v[0:1], 0, v[4:5]
	global_store_short v[4:5], v6, off
	v_add_u32_e32 v4, s0, v3
	v_lshl_add_u32 v3, v2, 2, v7
	ds_read_b32 v3, v3
	v_ashrrev_i32_e32 v5, 31, v4
	v_lshlrev_b64 v[4:5], 11, v[4:5]
	s_waitcnt lgkmcnt(1)
	v_cvt_pk_bf16_f32 v6, v8, s0
	v_lshl_add_u64 v[4:5], v[0:1], 0, v[4:5]
	v_add_u32_e32 v2, s0, v2
	global_store_short v[4:5], v6, off
	s_waitcnt lgkmcnt(0)
	v_cvt_pk_bf16_f32 v4, v3, s0
	v_ashrrev_i32_e32 v3, 31, v2
	v_lshlrev_b64 v[2:3], 11, v[2:3]
	v_lshl_add_u64 v[0:1], v[0:1], 0, v[2:3]
	global_store_short v[0:1], v4, off
	s_barrier
	s_mov_b64 s[0:1], 0
.LBB0_58:
	s_andn2_b64 vcc, exec, s[0:1]
	s_cbranch_vccnz .LBB0_60
	s_lshl_b32 s0, s3, 2
	s_and_b32 s0, s0, 0x3c0
	v_mov_b32_e32 v7, v211
	s_xor_b32 s1, s0, 0x200
	s_and_b32 s0, s2, 0x3c0
	s_lshl_b32 s2, s0, 2
	v_readlane_b32 s4, v254, 28
	v_ashrrev_i32_e32 v15, 6, v7
	v_and_b32_e32 v14, 63, v7
	s_add_u32 s4, s4, s2
	v_readlane_b32 s2, v254, 29
	v_add_u32_e32 v2, s1, v15
	s_addc_u32 s5, s2, 0
	v_lshlrev_b32_e32 v208, 2, v14
	v_ashrrev_i32_e32 v3, 31, v2
	v_lshl_add_u64 v[0:1], s[4:5], 0, v[208:209]
	v_lshlrev_b64 v[2:3], 12, v[2:3]
	v_lshl_add_u64 v[2:3], v[0:1], 0, v[2:3]
	global_load_dword v16, v[2:3], off nt
	v_add_u32_e32 v2, 0x100, v7
	v_ashrrev_i32_e32 v17, 6, v2
	v_add_u32_e32 v2, s1, v17
	v_ashrrev_i32_e32 v3, 31, v2
	v_lshlrev_b64 v[2:3], 12, v[2:3]
	v_lshl_add_u64 v[2:3], v[0:1], 0, v[2:3]
	global_load_dword v18, v[2:3], off nt
	v_add_u32_e32 v2, 0x200, v7
	v_ashrrev_i32_e32 v19, 6, v2
	v_add_u32_e32 v2, s1, v19
	v_ashrrev_i32_e32 v3, 31, v2
	v_lshlrev_b64 v[2:3], 12, v[2:3]
	v_lshl_add_u64 v[2:3], v[0:1], 0, v[2:3]
	global_load_dword v20, v[2:3], off nt
	v_add_u32_e32 v2, 0x300, v7
	v_ashrrev_i32_e32 v21, 6, v2
	v_add_u32_e32 v2, s1, v21
	v_ashrrev_i32_e32 v3, 31, v2
	v_lshlrev_b64 v[2:3], 12, v[2:3]
	v_lshl_add_u64 v[2:3], v[0:1], 0, v[2:3]
	global_load_dword v22, v[2:3], off nt
	v_add_u32_e32 v2, 0x400, v7
	v_ashrrev_i32_e32 v23, 6, v2
	v_add_u32_e32 v2, s1, v23
	v_ashrrev_i32_e32 v3, 31, v2
	v_lshlrev_b64 v[2:3], 12, v[2:3]
	v_lshl_add_u64 v[2:3], v[0:1], 0, v[2:3]
	global_load_dword v24, v[2:3], off nt
	v_add_u32_e32 v2, 0x500, v7
	v_ashrrev_i32_e32 v25, 6, v2
	v_add_u32_e32 v2, s1, v25
	v_ashrrev_i32_e32 v3, 31, v2
	v_lshlrev_b64 v[2:3], 12, v[2:3]
	v_lshl_add_u64 v[2:3], v[0:1], 0, v[2:3]
	global_load_dword v26, v[2:3], off nt
	v_add_u32_e32 v2, 0x600, v7
	v_ashrrev_i32_e32 v27, 6, v2
	v_add_u32_e32 v2, s1, v27
	v_ashrrev_i32_e32 v3, 31, v2
	v_lshlrev_b64 v[2:3], 12, v[2:3]
	v_lshl_add_u64 v[2:3], v[0:1], 0, v[2:3]
	global_load_dword v28, v[2:3], off nt
	v_add_u32_e32 v2, 0x700, v7
	v_ashrrev_i32_e32 v9, 6, v2
	v_add_u32_e32 v2, s1, v9
	v_ashrrev_i32_e32 v3, 31, v2
	v_lshlrev_b64 v[2:3], 12, v[2:3]
	v_lshl_add_u64 v[2:3], v[0:1], 0, v[2:3]
	global_load_dword v29, v[2:3], off nt
	v_add_u32_e32 v2, 0x800, v7
	v_ashrrev_i32_e32 v11, 6, v2
	v_add_u32_e32 v2, s1, v11
	v_ashrrev_i32_e32 v3, 31, v2
	v_lshlrev_b64 v[2:3], 12, v[2:3]
	v_lshl_add_u64 v[2:3], v[0:1], 0, v[2:3]
	global_load_dword v30, v[2:3], off nt
	v_add_u32_e32 v2, 0x900, v7
	v_ashrrev_i32_e32 v10, 6, v2
	v_add_u32_e32 v2, s1, v10
	v_ashrrev_i32_e32 v3, 31, v2
	v_lshlrev_b64 v[2:3], 12, v[2:3]
	v_lshl_add_u64 v[2:3], v[0:1], 0, v[2:3]
	global_load_dword v31, v[2:3], off nt
	v_add_u32_e32 v2, 0xa00, v7
	v_ashrrev_i32_e32 v8, 6, v2
	v_add_u32_e32 v2, s1, v8
	v_ashrrev_i32_e32 v3, 31, v2
	v_lshlrev_b64 v[2:3], 12, v[2:3]
	v_lshl_add_u64 v[2:3], v[0:1], 0, v[2:3]
	global_load_dword v32, v[2:3], off nt
	v_add_u32_e32 v2, 0xb00, v7
	v_ashrrev_i32_e32 v6, 6, v2
	v_add_u32_e32 v2, s1, v6
	v_ashrrev_i32_e32 v3, 31, v2
	v_lshlrev_b64 v[2:3], 12, v[2:3]
	v_lshl_add_u64 v[2:3], v[0:1], 0, v[2:3]
	global_load_dword v33, v[2:3], off nt
	v_add_u32_e32 v2, 0xc00, v7
	v_ashrrev_i32_e32 v5, 6, v2
	v_add_u32_e32 v2, s1, v5
	v_ashrrev_i32_e32 v3, 31, v2
	v_lshlrev_b64 v[2:3], 12, v[2:3]
	v_lshl_add_u64 v[2:3], v[0:1], 0, v[2:3]
	global_load_dword v34, v[2:3], off nt
	v_add_u32_e32 v2, 0xd00, v7
	v_ashrrev_i32_e32 v4, 6, v2
	v_add_u32_e32 v2, s1, v4
	v_ashrrev_i32_e32 v3, 31, v2
	v_lshlrev_b64 v[2:3], 12, v[2:3]
	v_lshl_add_u64 v[2:3], v[0:1], 0, v[2:3]
	global_load_dword v35, v[2:3], off nt
	v_add_u32_e32 v2, 0xe00, v7
	v_ashrrev_i32_e32 v3, 6, v2
	v_add_u32_e32 v12, s1, v3
	v_ashrrev_i32_e32 v13, 31, v12
	v_lshlrev_b64 v[12:13], 12, v[12:13]
	v_add_u32_e32 v2, 0xf00, v7
	v_lshl_add_u64 v[12:13], v[0:1], 0, v[12:13]
	v_ashrrev_i32_e32 v2, 6, v2
	global_load_dword v36, v[12:13], off nt
	v_add_u32_e32 v12, s1, v2
	v_ashrrev_i32_e32 v13, 31, v12
	v_lshlrev_b64 v[12:13], 12, v[12:13]
	v_lshl_add_u64 v[0:1], v[0:1], 0, v[12:13]
	global_load_dword v7, v[0:1], off nt
	v_add_u32_e32 v0, 0, v208
	v_mad_u64_u32 v[12:13], s[4:5], v15, s24, v[0:1]
	s_waitcnt vmcnt(15)
	ds_write_b32 v12, v16
	v_mad_u64_u32 v[12:13], s[4:5], v17, s24, v[0:1]
	s_waitcnt vmcnt(14)
	ds_write_b32 v12, v18
	v_mad_u64_u32 v[12:13], s[4:5], v19, s24, v[0:1]
	s_waitcnt vmcnt(13)
	ds_write_b32 v12, v20
	v_mad_u64_u32 v[12:13], s[4:5], v21, s24, v[0:1]
	s_waitcnt vmcnt(12)
	ds_write_b32 v12, v22
	v_mad_u64_u32 v[12:13], s[4:5], v23, s24, v[0:1]
	s_waitcnt vmcnt(11)
	ds_write_b32 v12, v24
	v_mad_u64_u32 v[12:13], s[4:5], v25, s24, v[0:1]
	s_waitcnt vmcnt(10)
	ds_write_b32 v12, v26
	v_mad_u64_u32 v[12:13], s[4:5], v27, s24, v[0:1]
	s_waitcnt vmcnt(9)
	ds_write_b32 v12, v28
	v_mad_u64_u32 v[12:13], s[4:5], v9, s24, v[0:1]
	s_waitcnt vmcnt(8)
	ds_write_b32 v12, v29
	v_mad_u64_u32 v[12:13], s[4:5], v11, s24, v[0:1]
	s_lshl_b32 s1, s1, 1
	v_readlane_b32 s2, v252, 11
	v_lshlrev_b32_e32 v208, 1, v14
	s_waitcnt vmcnt(7)
	ds_write_b32 v12, v30
	v_mad_u64_u32 v[12:13], s[4:5], v10, s24, v[0:1]
	s_waitcnt vmcnt(6)
	ds_write_b32 v12, v31
	v_mad_u64_u32 v[12:13], s[4:5], v8, s24, v[0:1]
	s_waitcnt vmcnt(5)
	ds_write_b32 v12, v32
	v_mad_u64_u32 v[12:13], s[4:5], v6, s24, v[0:1]
	s_waitcnt vmcnt(4)
	ds_write_b32 v12, v33
	v_mad_u64_u32 v[12:13], s[4:5], v5, s24, v[0:1]
	s_waitcnt vmcnt(3)
	ds_write_b32 v12, v34
	v_mad_u64_u32 v[12:13], s[4:5], v4, s24, v[0:1]
	s_waitcnt vmcnt(2)
	ds_write_b32 v12, v35
	v_mad_u64_u32 v[12:13], s[4:5], v3, s24, v[0:1]
	v_mad_u64_u32 v[0:1], s[4:5], v2, s24, v[0:1]
	s_add_u32 s4, s2, s1
	v_readlane_b32 s1, v252, 12
	s_addc_u32 s5, s1, 0
	s_waitcnt vmcnt(1)
	ds_write_b32 v12, v36
	s_waitcnt vmcnt(0)
	ds_write_b32 v0, v7
	v_mad_u32_u24 v7, v14, s24, 0
	v_lshl_add_u32 v0, v15, 2, v7
	s_waitcnt lgkmcnt(0)
	s_barrier
	ds_read_b32 v12, v0
	v_lshl_add_u32 v13, v17, 2, v7
	v_lshl_add_u64 v[0:1], s[4:5], 0, v[208:209]
	s_waitcnt lgkmcnt(0)
	v_cvt_pk_bf16_f32 v14, v12, s0
	v_add_u32_e32 v12, s0, v15
	ds_read_b32 v15, v13
	v_ashrrev_i32_e32 v13, 31, v12
	v_lshlrev_b64 v[12:13], 11, v[12:13]
	v_lshl_add_u64 v[12:13], v[0:1], 0, v[12:13]
	global_store_short v[12:13], v14, off
	v_lshl_add_u32 v13, v19, 2, v7
	s_waitcnt lgkmcnt(0)
	v_cvt_pk_bf16_f32 v14, v15, s0
	v_add_u32_e32 v12, s0, v17
	ds_read_b32 v15, v13
	v_ashrrev_i32_e32 v13, 31, v12
	v_lshlrev_b64 v[12:13], 11, v[12:13]
	v_lshl_add_u64 v[12:13], v[0:1], 0, v[12:13]
	global_store_short v[12:13], v14, off
	v_lshl_add_u32 v13, v21, 2, v7
	s_waitcnt lgkmcnt(0)
	v_cvt_pk_bf16_f32 v14, v15, s0
	v_add_u32_e32 v12, s0, v19
	ds_read_b32 v15, v13
	v_ashrrev_i32_e32 v13, 31, v12
	v_lshlrev_b64 v[12:13], 11, v[12:13]
	v_lshl_add_u64 v[12:13], v[0:1], 0, v[12:13]
	global_store_short v[12:13], v14, off
	v_lshl_add_u32 v13, v23, 2, v7
	s_waitcnt lgkmcnt(0)
	v_cvt_pk_bf16_f32 v14, v15, s0
	v_add_u32_e32 v12, s0, v21
	ds_read_b32 v15, v13
	v_ashrrev_i32_e32 v13, 31, v12
	v_lshlrev_b64 v[12:13], 11, v[12:13]
	v_lshl_add_u64 v[12:13], v[0:1], 0, v[12:13]
	global_store_short v[12:13], v14, off
	v_lshl_add_u32 v13, v25, 2, v7
	s_waitcnt lgkmcnt(0)
	v_cvt_pk_bf16_f32 v14, v15, s0
	v_add_u32_e32 v12, s0, v23
	ds_read_b32 v15, v13
	v_ashrrev_i32_e32 v13, 31, v12
	v_lshlrev_b64 v[12:13], 11, v[12:13]
	v_lshl_add_u64 v[12:13], v[0:1], 0, v[12:13]
	global_store_short v[12:13], v14, off
	v_lshl_add_u32 v13, v27, 2, v7
	s_waitcnt lgkmcnt(0)
	v_cvt_pk_bf16_f32 v14, v15, s0
	v_add_u32_e32 v12, s0, v25
	ds_read_b32 v15, v13
	v_ashrrev_i32_e32 v13, 31, v12
	v_lshlrev_b64 v[12:13], 11, v[12:13]
	v_lshl_add_u64 v[12:13], v[0:1], 0, v[12:13]
	global_store_short v[12:13], v14, off
	v_add_u32_e32 v12, s0, v27
	v_lshl_add_u32 v13, v9, 2, v7
	s_waitcnt lgkmcnt(0)
	v_cvt_pk_bf16_f32 v14, v15, s0
	ds_read_b32 v15, v13
	v_ashrrev_i32_e32 v13, 31, v12
	v_lshlrev_b64 v[12:13], 11, v[12:13]
	v_lshl_add_u64 v[12:13], v[0:1], 0, v[12:13]
	global_store_short v[12:13], v14, off
	v_add_u32_e32 v12, s0, v9
	v_ashrrev_i32_e32 v13, 31, v12
	v_lshlrev_b64 v[12:13], 11, v[12:13]
	s_waitcnt lgkmcnt(0)
	v_cvt_pk_bf16_f32 v14, v15, s0
	v_lshl_add_u32 v9, v11, 2, v7
	v_lshl_add_u64 v[12:13], v[0:1], 0, v[12:13]
	ds_read_b32 v9, v9
	global_store_short v[12:13], v14, off
	v_add_u32_e32 v12, s0, v11
	v_lshl_add_u32 v11, v10, 2, v7
	ds_read_b32 v11, v11
	v_ashrrev_i32_e32 v13, 31, v12
	v_lshlrev_b64 v[12:13], 11, v[12:13]
	s_waitcnt lgkmcnt(1)
	v_cvt_pk_bf16_f32 v9, v9, s0
	v_lshl_add_u64 v[12:13], v[0:1], 0, v[12:13]
	global_store_short v[12:13], v9, off
	s_waitcnt lgkmcnt(0)
	v_cvt_pk_bf16_f32 v9, v11, s0
	v_add_u32_e32 v10, s0, v10
	v_lshl_add_u32 v11, v8, 2, v7
	ds_read_b32 v12, v11
	v_ashrrev_i32_e32 v11, 31, v10
	v_lshlrev_b64 v[10:11], 11, v[10:11]
	v_lshl_add_u64 v[10:11], v[0:1], 0, v[10:11]
	global_store_short v[10:11], v9, off
	v_add_u32_e32 v8, s0, v8
	v_lshl_add_u32 v9, v6, 2, v7
	ds_read_b32 v11, v9
	v_ashrrev_i32_e32 v9, 31, v8
	v_lshlrev_b64 v[8:9], 11, v[8:9]
	s_waitcnt lgkmcnt(1)
	v_cvt_pk_bf16_f32 v10, v12, s0
	v_lshl_add_u64 v[8:9], v[0:1], 0, v[8:9]
	global_store_short v[8:9], v10, off
	v_add_u32_e32 v8, s0, v6
	v_ashrrev_i32_e32 v9, 31, v8
	v_lshlrev_b64 v[8:9], 11, v[8:9]
	s_waitcnt lgkmcnt(0)
	v_cvt_pk_bf16_f32 v10, v11, s0
	v_lshl_add_u32 v6, v5, 2, v7
	v_lshl_add_u64 v[8:9], v[0:1], 0, v[8:9]
	ds_read_b32 v6, v6
	global_store_short v[8:9], v10, off
	v_add_u32_e32 v8, s0, v5
	v_lshl_add_u32 v5, v4, 2, v7
	ds_read_b32 v5, v5
	v_ashrrev_i32_e32 v9, 31, v8
	v_lshlrev_b64 v[8:9], 11, v[8:9]
	s_waitcnt lgkmcnt(1)
	v_cvt_pk_bf16_f32 v6, v6, s0
	v_lshl_add_u64 v[8:9], v[0:1], 0, v[8:9]
	global_store_short v[8:9], v6, off
	s_waitcnt lgkmcnt(0)
	v_cvt_pk_bf16_f32 v6, v5, s0
	v_add_u32_e32 v4, s0, v4
	v_lshl_add_u32 v5, v3, 2, v7
	ds_read_b32 v8, v5
	v_ashrrev_i32_e32 v5, 31, v4
	v_lshlrev_b64 v[4:5], 11, v[4:5]
	v_lshl_add_u64 v[4:5], v[0:1], 0, v[4:5]
	global_store_short v[4:5], v6, off
	v_add_u32_e32 v4, s0, v3
	v_lshl_add_u32 v3, v2, 2, v7
	ds_read_b32 v3, v3
	v_ashrrev_i32_e32 v5, 31, v4
	v_lshlrev_b64 v[4:5], 11, v[4:5]
	s_waitcnt lgkmcnt(1)
	v_cvt_pk_bf16_f32 v6, v8, s0
	v_lshl_add_u64 v[4:5], v[0:1], 0, v[4:5]
	v_add_u32_e32 v2, s0, v2
	global_store_short v[4:5], v6, off
	s_waitcnt lgkmcnt(0)
	v_cvt_pk_bf16_f32 v4, v3, s0
	v_ashrrev_i32_e32 v3, 31, v2
	v_lshlrev_b64 v[2:3], 11, v[2:3]
	v_lshl_add_u64 v[0:1], v[0:1], 0, v[2:3]
	global_store_short v[0:1], v4, off
	s_barrier

.LBB0_61:
	s_andn2_b64 vcc, exec, s[0:1]
	s_cbranch_vccnz .LBB0_63
	s_add_i32 s0, s3, 0xfffffa00
	v_readlane_b32 s4, v254, 0
	s_lshr_b32 s4, s0, 7
	v_readlane_b32 s0, v254, 25
	s_add_u32 s0, s0, s4
	v_readlane_b32 s1, v254, 24
	s_addc_u32 s1, s1, 0
	s_lshl_b64 s[0:1], s[0:1], 21
	v_readlane_b32 s5, v254, 1
	s_add_u32 s7, s82, s0
	s_addc_u32 s9, s83, s1
	s_mov_b32 s1, s5
	v_writelane_b32 v254, s0, 0
	s_lshl_b64 s[4:5], s[4:5], 20
	v_mov_b32_e32 v7, v211
	v_writelane_b32 v254, s1, 1
	v_readlane_b32 s0, v252, 13
	s_add_u32 s1, s0, s4
	v_readlane_b32 s0, v252, 14
	s_addc_u32 s2, s0, s5
	s_lshl_b32 s0, s3, 2
	s_and_b32 s4, s0, 0x1c0
	s_lshl_b32 s0, s3, 6
	s_and_b32 s0, s0, 0x3c0
	s_lshl_b32 s5, s0, 2
	v_ashrrev_i32_e32 v15, 6, v7
	v_and_b32_e32 v14, 63, v7
	s_add_u32 s8, s7, s5
	v_add_u32_e32 v2, s4, v15
	s_addc_u32 s9, s9, 0
	v_lshlrev_b32_e32 v208, 2, v14
	v_ashrrev_i32_e32 v3, 31, v2
	v_lshl_add_u64 v[0:1], s[8:9], 0, v[208:209]
	v_lshlrev_b64 v[2:3], 12, v[2:3]
	v_lshl_add_u64 v[2:3], v[0:1], 0, v[2:3]
	global_load_dword v16, v[2:3], off nt
	v_add_u32_e32 v2, 0x100, v7
	v_ashrrev_i32_e32 v17, 6, v2
	v_add_u32_e32 v2, s4, v17
	v_ashrrev_i32_e32 v3, 31, v2
	v_lshlrev_b64 v[2:3], 12, v[2:3]
	v_lshl_add_u64 v[2:3], v[0:1], 0, v[2:3]
	global_load_dword v18, v[2:3], off nt
	v_add_u32_e32 v2, 0x200, v7
	v_ashrrev_i32_e32 v19, 6, v2
	v_add_u32_e32 v2, s4, v19
	v_ashrrev_i32_e32 v3, 31, v2
	v_lshlrev_b64 v[2:3], 12, v[2:3]
	v_lshl_add_u64 v[2:3], v[0:1], 0, v[2:3]
	global_load_dword v20, v[2:3], off nt
	v_add_u32_e32 v2, 0x300, v7
	v_ashrrev_i32_e32 v21, 6, v2
	v_add_u32_e32 v2, s4, v21
	v_ashrrev_i32_e32 v3, 31, v2
	v_lshlrev_b64 v[2:3], 12, v[2:3]
	v_lshl_add_u64 v[2:3], v[0:1], 0, v[2:3]
	global_load_dword v22, v[2:3], off nt
	v_add_u32_e32 v2, 0x400, v7
	v_ashrrev_i32_e32 v23, 6, v2
	v_add_u32_e32 v2, s4, v23
	v_ashrrev_i32_e32 v3, 31, v2
	v_lshlrev_b64 v[2:3], 12, v[2:3]
	v_lshl_add_u64 v[2:3], v[0:1], 0, v[2:3]
	global_load_dword v24, v[2:3], off nt
	v_add_u32_e32 v2, 0x500, v7
	v_ashrrev_i32_e32 v25, 6, v2
	v_add_u32_e32 v2, s4, v25
	v_ashrrev_i32_e32 v3, 31, v2
	v_lshlrev_b64 v[2:3], 12, v[2:3]
	v_lshl_add_u64 v[2:3], v[0:1], 0, v[2:3]
	global_load_dword v26, v[2:3], off nt
	v_add_u32_e32 v2, 0x600, v7
	v_ashrrev_i32_e32 v27, 6, v2
	v_add_u32_e32 v2, s4, v27
	v_ashrrev_i32_e32 v3, 31, v2
	v_lshlrev_b64 v[2:3], 12, v[2:3]
	v_lshl_add_u64 v[2:3], v[0:1], 0, v[2:3]
	global_load_dword v28, v[2:3], off nt
	v_add_u32_e32 v2, 0x700, v7
	v_ashrrev_i32_e32 v9, 6, v2
	v_add_u32_e32 v2, s4, v9
	v_ashrrev_i32_e32 v3, 31, v2
	v_lshlrev_b64 v[2:3], 12, v[2:3]
	v_lshl_add_u64 v[2:3], v[0:1], 0, v[2:3]
	global_load_dword v29, v[2:3], off nt
	v_add_u32_e32 v2, 0x800, v7
	v_ashrrev_i32_e32 v11, 6, v2
	v_add_u32_e32 v2, s4, v11
	v_ashrrev_i32_e32 v3, 31, v2
	v_lshlrev_b64 v[2:3], 12, v[2:3]
	v_lshl_add_u64 v[2:3], v[0:1], 0, v[2:3]
	global_load_dword v30, v[2:3], off nt
	v_add_u32_e32 v2, 0x900, v7
	v_ashrrev_i32_e32 v10, 6, v2
	v_add_u32_e32 v2, s4, v10
	v_ashrrev_i32_e32 v3, 31, v2
	v_lshlrev_b64 v[2:3], 12, v[2:3]
	v_lshl_add_u64 v[2:3], v[0:1], 0, v[2:3]
	global_load_dword v31, v[2:3], off nt
	v_add_u32_e32 v2, 0xa00, v7
	v_ashrrev_i32_e32 v8, 6, v2
	v_add_u32_e32 v2, s4, v8
	v_ashrrev_i32_e32 v3, 31, v2
	v_lshlrev_b64 v[2:3], 12, v[2:3]
	v_lshl_add_u64 v[2:3], v[0:1], 0, v[2:3]
	global_load_dword v32, v[2:3], off nt
	v_add_u32_e32 v2, 0xb00, v7
	v_ashrrev_i32_e32 v6, 6, v2
	v_add_u32_e32 v2, s4, v6
	v_ashrrev_i32_e32 v3, 31, v2
	v_lshlrev_b64 v[2:3], 12, v[2:3]
	v_lshl_add_u64 v[2:3], v[0:1], 0, v[2:3]
	global_load_dword v33, v[2:3], off nt
	v_add_u32_e32 v2, 0xc00, v7
	v_ashrrev_i32_e32 v5, 6, v2
	v_add_u32_e32 v2, s4, v5
	v_ashrrev_i32_e32 v3, 31, v2
	v_lshlrev_b64 v[2:3], 12, v[2:3]
	v_lshl_add_u64 v[2:3], v[0:1], 0, v[2:3]
	global_load_dword v34, v[2:3], off nt
	v_add_u32_e32 v2, 0xd00, v7
	v_ashrrev_i32_e32 v4, 6, v2
	v_add_u32_e32 v2, s4, v4
	v_ashrrev_i32_e32 v3, 31, v2
	v_lshlrev_b64 v[2:3], 12, v[2:3]
	v_lshl_add_u64 v[2:3], v[0:1], 0, v[2:3]
	global_load_dword v35, v[2:3], off nt
	v_add_u32_e32 v2, 0xe00, v7
	v_ashrrev_i32_e32 v3, 6, v2
	v_add_u32_e32 v12, s4, v3
	v_ashrrev_i32_e32 v13, 31, v12
	v_lshlrev_b64 v[12:13], 12, v[12:13]
	v_add_u32_e32 v2, 0xf00, v7
	v_lshl_add_u64 v[12:13], v[0:1], 0, v[12:13]
	v_ashrrev_i32_e32 v2, 6, v2
	global_load_dword v36, v[12:13], off nt
	v_add_u32_e32 v12, s4, v2
	v_ashrrev_i32_e32 v13, 31, v12
	v_lshlrev_b64 v[12:13], 12, v[12:13]
	v_lshl_add_u64 v[0:1], v[0:1], 0, v[12:13]
	global_load_dword v7, v[0:1], off nt
	v_add_u32_e32 v0, 0, v208
	v_mad_u64_u32 v[12:13], s[8:9], v15, s24, v[0:1]
	s_waitcnt vmcnt(15)
	ds_write_b32 v12, v16
	v_mad_u64_u32 v[12:13], s[8:9], v17, s24, v[0:1]
	s_waitcnt vmcnt(14)
	ds_write_b32 v12, v18
	v_mad_u64_u32 v[12:13], s[8:9], v19, s24, v[0:1]
	s_waitcnt vmcnt(13)
	ds_write_b32 v12, v20
	v_mad_u64_u32 v[12:13], s[8:9], v21, s24, v[0:1]
	s_waitcnt vmcnt(12)
	ds_write_b32 v12, v22
	v_mad_u64_u32 v[12:13], s[8:9], v23, s24, v[0:1]
	s_waitcnt vmcnt(11)
	ds_write_b32 v12, v24
	v_mad_u64_u32 v[12:13], s[8:9], v25, s24, v[0:1]
	s_waitcnt vmcnt(10)
	ds_write_b32 v12, v26
	v_mad_u64_u32 v[12:13], s[8:9], v27, s24, v[0:1]
	s_waitcnt vmcnt(9)
	ds_write_b32 v12, v28
	v_mad_u64_u32 v[12:13], s[8:9], v9, s24, v[0:1]
	s_waitcnt vmcnt(8)
	ds_write_b32 v12, v29
	v_mad_u64_u32 v[12:13], s[8:9], v11, s24, v[0:1]
	s_lshl_b32 s4, s4, 1
	s_add_u32 s4, s1, s4
	v_lshlrev_b32_e32 v208, 1, v14
	s_waitcnt vmcnt(7)
	ds_write_b32 v12, v30
	v_mad_u64_u32 v[12:13], s[8:9], v10, s24, v[0:1]
	s_addc_u32 s5, s2, 0
	s_waitcnt vmcnt(6)
	ds_write_b32 v12, v31
	v_mad_u64_u32 v[12:13], s[8:9], v8, s24, v[0:1]
	s_waitcnt vmcnt(5)
	ds_write_b32 v12, v32
	v_mad_u64_u32 v[12:13], s[8:9], v6, s24, v[0:1]
	s_waitcnt vmcnt(4)
	ds_write_b32 v12, v33
	v_mad_u64_u32 v[12:13], s[8:9], v5, s24, v[0:1]
	s_waitcnt vmcnt(3)
	ds_write_b32 v12, v34
	v_mad_u64_u32 v[12:13], s[8:9], v4, s24, v[0:1]
	s_waitcnt vmcnt(2)
	ds_write_b32 v12, v35
	v_mad_u64_u32 v[12:13], s[8:9], v3, s24, v[0:1]
	v_mad_u64_u32 v[0:1], s[8:9], v2, s24, v[0:1]
	s_waitcnt vmcnt(1)
	ds_write_b32 v12, v36
	s_waitcnt vmcnt(0)
	ds_write_b32 v0, v7
	v_mad_u32_u24 v7, v14, s24, 0
	v_lshl_add_u32 v0, v15, 2, v7
	s_waitcnt lgkmcnt(0)
	s_barrier
	ds_read_b32 v12, v0
	v_lshl_add_u32 v13, v17, 2, v7
	v_lshl_add_u64 v[0:1], s[4:5], 0, v[208:209]
	s_waitcnt lgkmcnt(0)
	v_cvt_pk_bf16_f32 v14, v12, s0
	v_add_u32_e32 v12, s0, v15
	ds_read_b32 v15, v13
	v_ashrrev_i32_e32 v13, 31, v12
	v_lshlrev_b64 v[12:13], 10, v[12:13]
	v_lshl_add_u64 v[12:13], v[0:1], 0, v[12:13]
	global_store_short v[12:13], v14, off
	v_lshl_add_u32 v13, v19, 2, v7
	s_waitcnt lgkmcnt(0)
	v_cvt_pk_bf16_f32 v14, v15, s0
	v_add_u32_e32 v12, s0, v17
	ds_read_b32 v15, v13
	v_ashrrev_i32_e32 v13, 31, v12
	v_lshlrev_b64 v[12:13], 10, v[12:13]
	v_lshl_add_u64 v[12:13], v[0:1], 0, v[12:13]
	global_store_short v[12:13], v14, off
	v_lshl_add_u32 v13, v21, 2, v7
	s_waitcnt lgkmcnt(0)
	v_cvt_pk_bf16_f32 v14, v15, s0
	v_add_u32_e32 v12, s0, v19
	ds_read_b32 v15, v13
	v_ashrrev_i32_e32 v13, 31, v12
	v_lshlrev_b64 v[12:13], 10, v[12:13]
	v_lshl_add_u64 v[12:13], v[0:1], 0, v[12:13]
	global_store_short v[12:13], v14, off
	v_lshl_add_u32 v13, v23, 2, v7
	s_waitcnt lgkmcnt(0)
	v_cvt_pk_bf16_f32 v14, v15, s0
	v_add_u32_e32 v12, s0, v21
	ds_read_b32 v15, v13
	v_ashrrev_i32_e32 v13, 31, v12
	v_lshlrev_b64 v[12:13], 10, v[12:13]
	v_lshl_add_u64 v[12:13], v[0:1], 0, v[12:13]
	global_store_short v[12:13], v14, off
	v_lshl_add_u32 v13, v25, 2, v7
	s_waitcnt lgkmcnt(0)
	v_cvt_pk_bf16_f32 v14, v15, s0
	v_add_u32_e32 v12, s0, v23
	ds_read_b32 v15, v13
	v_ashrrev_i32_e32 v13, 31, v12
	v_lshlrev_b64 v[12:13], 10, v[12:13]
	v_lshl_add_u64 v[12:13], v[0:1], 0, v[12:13]
	global_store_short v[12:13], v14, off
	v_lshl_add_u32 v13, v27, 2, v7
	s_waitcnt lgkmcnt(0)
	v_cvt_pk_bf16_f32 v14, v15, s0
	v_add_u32_e32 v12, s0, v25
	ds_read_b32 v15, v13
	v_ashrrev_i32_e32 v13, 31, v12
	v_lshlrev_b64 v[12:13], 10, v[12:13]
	v_lshl_add_u64 v[12:13], v[0:1], 0, v[12:13]
	global_store_short v[12:13], v14, off
	v_add_u32_e32 v12, s0, v27
	v_lshl_add_u32 v13, v9, 2, v7
	s_waitcnt lgkmcnt(0)
	v_cvt_pk_bf16_f32 v14, v15, s0
	ds_read_b32 v15, v13
	v_ashrrev_i32_e32 v13, 31, v12
	v_lshlrev_b64 v[12:13], 10, v[12:13]
	v_lshl_add_u64 v[12:13], v[0:1], 0, v[12:13]
	global_store_short v[12:13], v14, off
	v_add_u32_e32 v12, s0, v9
	v_ashrrev_i32_e32 v13, 31, v12
	v_lshlrev_b64 v[12:13], 10, v[12:13]
	s_waitcnt lgkmcnt(0)
	v_cvt_pk_bf16_f32 v14, v15, s0
	v_lshl_add_u32 v9, v11, 2, v7
	v_lshl_add_u64 v[12:13], v[0:1], 0, v[12:13]
	ds_read_b32 v9, v9
	global_store_short v[12:13], v14, off
	v_add_u32_e32 v12, s0, v11
	v_lshl_add_u32 v11, v10, 2, v7
	ds_read_b32 v11, v11
	v_ashrrev_i32_e32 v13, 31, v12
	v_lshlrev_b64 v[12:13], 10, v[12:13]
	s_waitcnt lgkmcnt(1)
	v_cvt_pk_bf16_f32 v9, v9, s0
	v_lshl_add_u64 v[12:13], v[0:1], 0, v[12:13]
	global_store_short v[12:13], v9, off
	s_waitcnt lgkmcnt(0)
	v_cvt_pk_bf16_f32 v9, v11, s0
	v_add_u32_e32 v10, s0, v10
	v_lshl_add_u32 v11, v8, 2, v7
	ds_read_b32 v12, v11
	v_ashrrev_i32_e32 v11, 31, v10
	v_lshlrev_b64 v[10:11], 10, v[10:11]
	v_lshl_add_u64 v[10:11], v[0:1], 0, v[10:11]
	global_store_short v[10:11], v9, off
	v_add_u32_e32 v8, s0, v8
	v_lshl_add_u32 v9, v6, 2, v7
	ds_read_b32 v11, v9
	v_ashrrev_i32_e32 v9, 31, v8
	v_lshlrev_b64 v[8:9], 10, v[8:9]
	s_waitcnt lgkmcnt(1)
	v_cvt_pk_bf16_f32 v10, v12, s0
	v_lshl_add_u64 v[8:9], v[0:1], 0, v[8:9]
	global_store_short v[8:9], v10, off
	v_add_u32_e32 v8, s0, v6
	v_ashrrev_i32_e32 v9, 31, v8
	v_lshlrev_b64 v[8:9], 10, v[8:9]
	s_waitcnt lgkmcnt(0)
	v_cvt_pk_bf16_f32 v10, v11, s0
	v_lshl_add_u32 v6, v5, 2, v7
	v_lshl_add_u64 v[8:9], v[0:1], 0, v[8:9]
	ds_read_b32 v6, v6
	global_store_short v[8:9], v10, off
	v_add_u32_e32 v8, s0, v5
	v_lshl_add_u32 v5, v4, 2, v7
	ds_read_b32 v5, v5
	v_ashrrev_i32_e32 v9, 31, v8
	v_lshlrev_b64 v[8:9], 10, v[8:9]
	s_waitcnt lgkmcnt(1)
	v_cvt_pk_bf16_f32 v6, v6, s0
	v_lshl_add_u64 v[8:9], v[0:1], 0, v[8:9]
	global_store_short v[8:9], v6, off
	s_waitcnt lgkmcnt(0)
	v_cvt_pk_bf16_f32 v6, v5, s0
	v_add_u32_e32 v4, s0, v4
	v_lshl_add_u32 v5, v3, 2, v7
	ds_read_b32 v8, v5
	v_ashrrev_i32_e32 v5, 31, v4
	v_lshlrev_b64 v[4:5], 10, v[4:5]
	v_lshl_add_u64 v[4:5], v[0:1], 0, v[4:5]
	global_store_short v[4:5], v6, off
	v_add_u32_e32 v4, s0, v3
	v_lshl_add_u32 v3, v2, 2, v7
	ds_read_b32 v3, v3
	v_ashrrev_i32_e32 v5, 31, v4
	v_lshlrev_b64 v[4:5], 10, v[4:5]
	s_waitcnt lgkmcnt(1)
	v_cvt_pk_bf16_f32 v6, v8, s0
	v_lshl_add_u64 v[4:5], v[0:1], 0, v[4:5]
	v_add_u32_e32 v2, s0, v2
	global_store_short v[4:5], v6, off
	s_waitcnt lgkmcnt(0)
	v_cvt_pk_bf16_f32 v4, v3, s0
	v_ashrrev_i32_e32 v3, 31, v2
	v_lshlrev_b64 v[2:3], 10, v[2:3]
	v_lshl_add_u64 v[0:1], v[0:1], 0, v[2:3]
	global_store_short v[0:1], v4, off
	s_barrier

.LBB0_64:
	s_andn2_b64 vcc, exec, s[0:1]
	s_cbranch_vccnz .LBB0_66
	s_sext_i32_i16 s0, s3
	s_mulk_i32 s0, 0x2aab
	s_lshr_b32 s1, s0, 31
	s_ashr_i32 s0, s0, 20
	s_add_i32 s0, s0, s1
	s_lshl_b32 s2, s0, 6
	s_mulk_i32 s0, 0x60
	s_sub_i32 s0, s3, s0
	s_sext_i32_i16 s0, s0
	s_lshl_b32 s0, s0, 6
	s_ashr_i32 s1, s0, 31
	v_mov_b32_e32 v1, v211
	s_lshl_b64 s[4:5], s[0:1], 2
	v_readlane_b32 s1, v254, 30
	s_add_u32 s4, s1, s4
	v_and_b32_e32 v17, 63, v1
	v_readlane_b32 s1, v254, 31
	s_addc_u32 s5, s1, s5
	v_lshlrev_b32_e32 v208, 2, v17
	v_ashrrev_i32_e32 v20, 6, v1
	v_lshl_add_u64 v[2:3], s[4:5], 0, v[208:209]
	v_add_u32_e32 v4, s2, v20
	s_movk_i32 s1, 0x6000
	v_mad_i64_i32 v[4:5], s[4:5], v4, s1, v[2:3]
	global_load_dword v6, v[4:5], off nt
	v_add_u32_e32 v0, 0, v208
	v_mad_u64_u32 v[4:5], s[4:5], v20, s24, v[0:1]
	s_ashr_i32 s3, s2, 31
	v_lshlrev_b32_e32 v208, 1, v17
	s_waitcnt vmcnt(0)
	ds_write_b32 v4, v6
	v_add_u32_e32 v4, 0x100, v1
	v_ashrrev_i32_e32 v21, 6, v4
	v_add_u32_e32 v4, s2, v21
	v_mad_i64_i32 v[4:5], s[4:5], v4, s1, v[2:3]
	global_load_dword v6, v[4:5], off nt
	v_mad_u64_u32 v[4:5], s[4:5], v21, s24, v[0:1]
	s_waitcnt vmcnt(0)
	ds_write_b32 v4, v6
	v_add_u32_e32 v4, 0x200, v1
	v_ashrrev_i32_e32 v22, 6, v4
	v_add_u32_e32 v4, s2, v22
	v_mad_i64_i32 v[4:5], s[4:5], v4, s1, v[2:3]
	global_load_dword v6, v[4:5], off nt
	v_mad_u64_u32 v[4:5], s[4:5], v22, s24, v[0:1]
	s_waitcnt vmcnt(0)
	ds_write_b32 v4, v6
	v_add_u32_e32 v4, 0x300, v1
	v_ashrrev_i32_e32 v16, 6, v4
	v_add_u32_e32 v4, s2, v16
	v_mad_i64_i32 v[4:5], s[4:5], v4, s1, v[2:3]
	global_load_dword v6, v[4:5], off nt
	v_mad_u64_u32 v[4:5], s[4:5], v16, s24, v[0:1]
	s_waitcnt vmcnt(0)
	ds_write_b32 v4, v6
	v_add_u32_e32 v4, 0x400, v1
	v_ashrrev_i32_e32 v15, 6, v4
	v_add_u32_e32 v4, s2, v15
	v_mad_i64_i32 v[4:5], s[4:5], v4, s1, v[2:3]
	global_load_dword v6, v[4:5], off nt
	v_mad_u64_u32 v[4:5], s[4:5], v15, s24, v[0:1]
	s_waitcnt vmcnt(0)
	ds_write_b32 v4, v6
	v_add_u32_e32 v4, 0x500, v1
	v_ashrrev_i32_e32 v14, 6, v4
	v_add_u32_e32 v4, s2, v14
	v_mad_i64_i32 v[4:5], s[4:5], v4, s1, v[2:3]
	global_load_dword v6, v[4:5], off nt
	v_mad_u64_u32 v[4:5], s[4:5], v14, s24, v[0:1]
	s_waitcnt vmcnt(0)
	ds_write_b32 v4, v6
	v_add_u32_e32 v4, 0x600, v1
	v_ashrrev_i32_e32 v13, 6, v4
	v_add_u32_e32 v4, s2, v13
	v_mad_i64_i32 v[4:5], s[4:5], v4, s1, v[2:3]
	global_load_dword v6, v[4:5], off nt
	v_mad_u64_u32 v[4:5], s[4:5], v13, s24, v[0:1]
	s_waitcnt vmcnt(0)
	ds_write_b32 v4, v6
	v_add_u32_e32 v4, 0x700, v1
	v_ashrrev_i32_e32 v10, 6, v4
	v_add_u32_e32 v4, s2, v10
	v_mad_i64_i32 v[4:5], s[4:5], v4, s1, v[2:3]
	global_load_dword v6, v[4:5], off nt
	v_mad_u64_u32 v[4:5], s[4:5], v10, s24, v[0:1]
	s_waitcnt vmcnt(0)
	ds_write_b32 v4, v6
	v_add_u32_e32 v4, 0x800, v1
	v_ashrrev_i32_e32 v12, 6, v4
	v_add_u32_e32 v4, s2, v12
	v_mad_i64_i32 v[4:5], s[4:5], v4, s1, v[2:3]
	global_load_dword v6, v[4:5], off nt
	v_mad_u64_u32 v[4:5], s[4:5], v12, s24, v[0:1]
	s_waitcnt vmcnt(0)
	ds_write_b32 v4, v6
	v_add_u32_e32 v4, 0x900, v1
	v_ashrrev_i32_e32 v11, 6, v4
	v_add_u32_e32 v4, s2, v11
	v_mad_i64_i32 v[4:5], s[4:5], v4, s1, v[2:3]
	global_load_dword v6, v[4:5], off nt
	v_mad_u64_u32 v[4:5], s[4:5], v11, s24, v[0:1]
	s_waitcnt vmcnt(0)
	ds_write_b32 v4, v6
	v_add_u32_e32 v4, 0xa00, v1
	v_ashrrev_i32_e32 v9, 6, v4
	v_add_u32_e32 v4, s2, v9
	v_mad_i64_i32 v[4:5], s[4:5], v4, s1, v[2:3]
	global_load_dword v6, v[4:5], off nt
	v_mad_u64_u32 v[4:5], s[4:5], v9, s24, v[0:1]
	s_waitcnt vmcnt(0)
	ds_write_b32 v4, v6
	v_add_u32_e32 v4, 0xb00, v1
	v_ashrrev_i32_e32 v8, 6, v4
	v_add_u32_e32 v4, s2, v8
	v_mad_i64_i32 v[4:5], s[4:5], v4, s1, v[2:3]
	global_load_dword v6, v[4:5], off nt
	v_mad_u64_u32 v[4:5], s[4:5], v8, s24, v[0:1]
	s_waitcnt vmcnt(0)
	ds_write_b32 v4, v6
	v_add_u32_e32 v4, 0xc00, v1
	v_ashrrev_i32_e32 v7, 6, v4
	v_add_u32_e32 v4, s2, v7
	v_mad_i64_i32 v[4:5], s[4:5], v4, s1, v[2:3]
	global_load_dword v6, v[4:5], off nt
	v_mad_u64_u32 v[4:5], s[4:5], v7, s24, v[0:1]
	s_waitcnt vmcnt(0)
	ds_write_b32 v4, v6
	v_add_u32_e32 v4, 0xd00, v1
	v_ashrrev_i32_e32 v6, 6, v4
	v_add_u32_e32 v4, s2, v6
	v_mad_i64_i32 v[4:5], s[4:5], v4, s1, v[2:3]
	global_load_dword v18, v[4:5], off nt
	v_mad_u64_u32 v[4:5], s[4:5], v6, s24, v[0:1]
	s_waitcnt vmcnt(0)
	ds_write_b32 v4, v18
	v_add_u32_e32 v4, 0xe00, v1
	v_ashrrev_i32_e32 v5, 6, v4
	v_add_u32_e32 v4, s2, v5
	v_mad_i64_i32 v[18:19], s[4:5], v4, s1, v[2:3]
	global_load_dword v4, v[18:19], off nt
	v_mad_u64_u32 v[18:19], s[4:5], v5, s24, v[0:1]
	v_add_u32_e32 v1, 0xf00, v1
	s_waitcnt vmcnt(0)
	ds_write_b32 v18, v4
	v_ashrrev_i32_e32 v4, 6, v1
	v_add_u32_e32 v1, s2, v4
	v_mad_i64_i32 v[2:3], s[4:5], v1, s1, v[2:3]
	global_load_dword v2, v[2:3], off nt
	v_mad_u64_u32 v[0:1], s[4:5], v4, s24, v[0:1]
	s_lshl_b64 s[2:3], s[2:3], 1
	s_add_u32 s2, s46, s2
	v_add_u32_e32 v18, s0, v20
	s_addc_u32 s3, s47, s3
	v_ashrrev_i32_e32 v19, 31, v18
	v_lshlrev_b64 v[18:19], 11, v[18:19]
	s_waitcnt vmcnt(0)
	ds_write_b32 v0, v2
	v_mad_u32_u24 v2, v17, s24, 0
	v_lshl_add_u32 v3, v20, 2, v2
	s_waitcnt lgkmcnt(0)
	s_barrier
	ds_read_b32 v3, v3
	v_lshl_add_u64 v[0:1], s[2:3], 0, v[208:209]
	v_lshl_add_u64 v[18:19], v[0:1], 0, v[18:19]
	s_waitcnt lgkmcnt(0)
	v_cvt_pk_bf16_f32 v3, v3, s0
	global_store_short v[18:19], v3, off
	v_lshl_add_u32 v3, v21, 2, v2
	ds_read_b32 v3, v3
	v_add_u32_e32 v18, s0, v21
	v_ashrrev_i32_e32 v19, 31, v18
	v_lshlrev_b64 v[18:19], 11, v[18:19]
	v_lshl_add_u64 v[18:19], v[0:1], 0, v[18:19]
	s_waitcnt lgkmcnt(0)
	v_cvt_pk_bf16_f32 v3, v3, s0
	global_store_short v[18:19], v3, off
	v_lshl_add_u32 v3, v22, 2, v2
	ds_read_b32 v3, v3
	v_add_u32_e32 v18, s0, v22
	v_ashrrev_i32_e32 v19, 31, v18
	v_lshlrev_b64 v[18:19], 11, v[18:19]
	v_lshl_add_u64 v[18:19], v[0:1], 0, v[18:19]
	s_waitcnt lgkmcnt(0)
	v_cvt_pk_bf16_f32 v3, v3, s0
	global_store_short v[18:19], v3, off
	v_lshl_add_u32 v3, v16, 2, v2
	ds_read_b32 v3, v3
	v_add_u32_e32 v16, s0, v16
	v_ashrrev_i32_e32 v17, 31, v16
	v_lshlrev_b64 v[16:17], 11, v[16:17]
	v_lshl_add_u64 v[16:17], v[0:1], 0, v[16:17]
	s_waitcnt lgkmcnt(0)
	v_cvt_pk_bf16_f32 v3, v3, s0
	global_store_short v[16:17], v3, off
	v_lshl_add_u32 v3, v15, 2, v2
	ds_read_b32 v3, v3
	v_add_u32_e32 v16, s0, v15
	v_ashrrev_i32_e32 v17, 31, v16
	v_lshlrev_b64 v[16:17], 11, v[16:17]
	v_lshl_add_u64 v[16:17], v[0:1], 0, v[16:17]
	s_waitcnt lgkmcnt(0)
	v_cvt_pk_bf16_f32 v3, v3, s0
	global_store_short v[16:17], v3, off
	v_lshl_add_u32 v3, v14, 2, v2
	ds_read_b32 v3, v3
	v_add_u32_e32 v14, s0, v14
	v_ashrrev_i32_e32 v15, 31, v14
	v_lshlrev_b64 v[14:15], 11, v[14:15]
	v_lshl_add_u64 v[14:15], v[0:1], 0, v[14:15]
	s_waitcnt lgkmcnt(0)
	v_cvt_pk_bf16_f32 v3, v3, s0
	global_store_short v[14:15], v3, off
	v_lshl_add_u32 v3, v13, 2, v2
	ds_read_b32 v3, v3
	v_add_u32_e32 v14, s0, v13
	v_ashrrev_i32_e32 v15, 31, v14
	v_lshlrev_b64 v[14:15], 11, v[14:15]
	v_lshl_add_u64 v[14:15], v[0:1], 0, v[14:15]
	s_waitcnt lgkmcnt(0)
	v_cvt_pk_bf16_f32 v3, v3, s0
	global_store_short v[14:15], v3, off
	v_lshl_add_u32 v3, v10, 2, v2
	ds_read_b32 v3, v3
	v_add_u32_e32 v14, s0, v10
	v_ashrrev_i32_e32 v15, 31, v14
	v_lshlrev_b64 v[14:15], 11, v[14:15]
	v_lshl_add_u64 v[14:15], v[0:1], 0, v[14:15]
	s_waitcnt lgkmcnt(0)
	v_cvt_pk_bf16_f32 v3, v3, s0
	global_store_short v[14:15], v3, off
	v_lshl_add_u32 v3, v12, 2, v2
	ds_read_b32 v3, v3
	v_add_u32_e32 v12, s0, v12
	v_ashrrev_i32_e32 v13, 31, v12
	v_lshlrev_b64 v[12:13], 11, v[12:13]
	v_lshl_add_u64 v[12:13], v[0:1], 0, v[12:13]
	s_waitcnt lgkmcnt(0)
	v_cvt_pk_bf16_f32 v3, v3, s0
	global_store_short v[12:13], v3, off
	v_lshl_add_u32 v3, v11, 2, v2
	ds_read_b32 v3, v3
	v_add_u32_e32 v10, s0, v11
	v_ashrrev_i32_e32 v11, 31, v10
	v_lshlrev_b64 v[10:11], 11, v[10:11]
	v_lshl_add_u64 v[10:11], v[0:1], 0, v[10:11]
	s_waitcnt lgkmcnt(0)
	v_cvt_pk_bf16_f32 v3, v3, s0
	global_store_short v[10:11], v3, off
	v_lshl_add_u32 v3, v9, 2, v2
	ds_read_b32 v3, v3
	v_add_u32_e32 v10, s0, v9
	v_ashrrev_i32_e32 v11, 31, v10
	v_lshlrev_b64 v[10:11], 11, v[10:11]
	v_lshl_add_u64 v[10:11], v[0:1], 0, v[10:11]
	s_waitcnt lgkmcnt(0)
	v_cvt_pk_bf16_f32 v3, v3, s0
	global_store_short v[10:11], v3, off
	v_lshl_add_u32 v3, v8, 2, v2
	ds_read_b32 v3, v3
	v_add_u32_e32 v8, s0, v8
	v_ashrrev_i32_e32 v9, 31, v8
	v_lshlrev_b64 v[8:9], 11, v[8:9]
	v_lshl_add_u64 v[8:9], v[0:1], 0, v[8:9]
	s_waitcnt lgkmcnt(0)
	v_cvt_pk_bf16_f32 v3, v3, s0
	global_store_short v[8:9], v3, off
	v_lshl_add_u32 v3, v7, 2, v2
	ds_read_b32 v3, v3
	v_add_u32_e32 v8, s0, v7
	v_ashrrev_i32_e32 v9, 31, v8
	v_lshlrev_b64 v[8:9], 11, v[8:9]
	v_lshl_add_u64 v[8:9], v[0:1], 0, v[8:9]
	s_waitcnt lgkmcnt(0)
	v_cvt_pk_bf16_f32 v3, v3, s0
	global_store_short v[8:9], v3, off
	v_lshl_add_u32 v3, v6, 2, v2
	ds_read_b32 v3, v3
	v_add_u32_e32 v6, s0, v6
	v_ashrrev_i32_e32 v7, 31, v6
	v_lshlrev_b64 v[6:7], 11, v[6:7]
	v_lshl_add_u64 v[6:7], v[0:1], 0, v[6:7]
	s_waitcnt lgkmcnt(0)
	v_cvt_pk_bf16_f32 v3, v3, s0
	global_store_short v[6:7], v3, off
	v_lshl_add_u32 v3, v5, 2, v2
	v_lshl_add_u32 v2, v4, 2, v2
	ds_read_b32 v3, v3
	ds_read_b32 v2, v2
	v_add_u32_e32 v6, s0, v5
	v_ashrrev_i32_e32 v7, 31, v6
	v_lshlrev_b64 v[6:7], 11, v[6:7]
	s_waitcnt lgkmcnt(1)
	v_cvt_pk_bf16_f32 v3, v3, s0
	v_lshl_add_u64 v[6:7], v[0:1], 0, v[6:7]
	s_waitcnt lgkmcnt(0)
	v_cvt_pk_bf16_f32 v5, v2, s0
	v_add_u32_e32 v2, s0, v4
	global_store_short v[6:7], v3, off
	v_ashrrev_i32_e32 v3, 31, v2
	v_lshlrev_b64 v[2:3], 11, v[2:3]
	v_lshl_add_u64 v[0:1], v[0:1], 0, v[2:3]
	global_store_short v[0:1], v5, off
	s_barrier
